# non-temporal hint also on the attn_store gate-row loads of the MLA and SWA attention epilogues
# speedup vs baseline: 1.0059x; 1.0059x over previous
.LBB0_1197:
	ds_bpermute_b32 v1, v180, v186
	s_ashr_i32 s54, s8, 3
	s_ashr_i32 s55, s54, 31
	s_load_dwordx4 s[8:11], s[0:1], 0x158
	s_lshl_b64 s[54:55], s[54:55], 12
	s_waitcnt lgkmcnt(0)
	v_add_f32_e32 v1, v186, v1
	v_div_scale_f32 v3, s[56:57], v1, v1, 1.0
	v_rcp_f32_e32 v4, v3
	v_div_scale_f32 v7, vcc, 1.0, v1, 1.0
	s_ashr_i32 s2, s52, 31
	v_fma_f32 v8, -v3, v4, 1.0
	v_fmac_f32_e32 v4, v8, v4
	v_mul_f32_e32 v8, v7, v4
	v_fma_f32 v11, -v3, v8, v7
	v_fmac_f32_e32 v8, v11, v4
	v_fma_f32 v3, -v3, v8, v7
	v_div_fmas_f32 v3, v3, v4, v8
	v_div_fixup_f32 v4, v3, v1, 1.0
	v_mov_b32_e32 v3, v178
	s_add_u32 s25, s54, s52
	v_add_u32_e32 v1, s70, v3
	s_addc_u32 s2, s55, s2
	v_readfirstlane_b32 s52, v1
	s_lshr_b32 s52, s52, 6
	s_mulk_i32 s52, 0x1200
	s_add_i32 s52, s52, 0x18000
	v_and_b32_e32 v1, 31, v3
	v_mov_b32_e32 v7, s52
	v_mad_u32_u24 v1, v1, s49, v7
	v_lshrrev_b32_e32 v7, 2, v3
	v_mul_f32_e32 v11, v50, v4
	v_pk_mul_f32 v[50:51], v[96:97], v[4:5] op_sel_hi:[1,0]
	s_lshl_b32 s24, s24, 7
	v_and_or_b32 v1, v7, 8, v1
	v_bfe_u32 v7, v3, 3, 3
	v_lshlrev_b32_e32 v3, 3, v3
	v_cvt_pk_bf16_f32 v11, v11, s0
	v_cvt_pk_bf16_f32 v12, v50, v51
	s_and_b32 s24, s24, 0x380
	v_and_b32_e32 v3, 56, v3
	v_perm_b32 v50, v12, v11, s50
	v_mul_f32_e32 v11, v53, v4
	v_lshl_or_b32 v8, v3, 1, s52
	v_or_b32_e32 v3, s24, v3
	v_cvt_pk_bf16_f32 v11, v11, s0
	s_waitcnt vmcnt(4)
	v_or_b32_e32 v98, s25, v7
	v_mov_b32_e32 v99, s2
	v_alignbit_b32 v51, v11, v12, 16
	v_lshlrev_b64 v[96:97], 11, v[98:99]
	v_lshlrev_b32_e32 v11, 1, v3
	v_or_b32_e32 v96, v96, v11
	v_lshl_add_u64 v[100:101], s[10:11], 0, v[96:97]
	ds_write_b64 v1, v[50:51]
	global_load_dwordx4 v[50:53], v[100:101], off nt
	v_mul_f32_e32 v3, v54, v4
	v_pk_mul_f32 v[54:55], v[92:93], v[4:5] op_sel_hi:[1,0]
	v_cvt_pk_bf16_f32 v3, v3, s0
	v_cvt_pk_bf16_f32 v12, v54, v55
	v_perm_b32 v54, v12, v3, s50
	v_mul_f32_e32 v3, v57, v4
	v_cvt_pk_bf16_f32 v3, v3, s0
	v_alignbit_b32 v55, v3, v12, 16
	ds_write_b64 v1, v[54:55] offset:16
	v_mul_f32_e32 v3, v58, v4
	v_pk_mul_f32 v[54:55], v[90:91], v[4:5] op_sel_hi:[1,0]
	v_cvt_pk_bf16_f32 v3, v3, s0
	v_cvt_pk_bf16_f32 v12, v54, v55
	v_perm_b32 v54, v12, v3, s50
	v_mul_f32_e32 v3, v61, v4
	v_cvt_pk_bf16_f32 v3, v3, s0
	v_alignbit_b32 v55, v3, v12, 16
	ds_write_b64 v1, v[54:55] offset:32
	v_mul_f32_e32 v3, v62, v4
	v_pk_mul_f32 v[54:55], v[88:89], v[4:5] op_sel_hi:[1,0]
	v_cvt_pk_bf16_f32 v3, v3, s0
	v_cvt_pk_bf16_f32 v12, v54, v55
	v_perm_b32 v54, v12, v3, s50
	v_mul_f32_e32 v3, v65, v4
	v_cvt_pk_bf16_f32 v3, v3, s0
	v_alignbit_b32 v55, v3, v12, 16
	v_mul_f32_e32 v3, v34, v4
	v_pk_mul_f32 v[34:35], v[94:95], v[4:5] op_sel_hi:[1,0]
	v_cvt_pk_bf16_f32 v3, v3, s0
	v_cvt_pk_bf16_f32 v12, v34, v35
	v_or_b32_e32 v34, 8, v98
	v_mov_b32_e32 v35, s2
	v_lshlrev_b64 v[58:59], 11, v[34:35]
	v_or_b32_e32 v58, v58, v11
	v_perm_b32 v34, v12, v3, s50
	v_mul_f32_e32 v3, v37, v4
	v_lshl_add_u64 v[62:63], s[10:11], 0, v[58:59]
	v_cvt_pk_bf16_f32 v3, v3, s0
	ds_write_b64 v1, v[54:55] offset:48
	global_load_dwordx4 v[54:57], v[62:63], off nt
	v_alignbit_b32 v35, v3, v12, 16
	ds_write_b64 v1, v[34:35] offset:64
	v_mul_f32_e32 v3, v38, v4
	v_pk_mul_f32 v[34:35], v[86:87], v[4:5] op_sel_hi:[1,0]
	v_cvt_pk_bf16_f32 v3, v3, s0
	v_cvt_pk_bf16_f32 v12, v34, v35
	v_perm_b32 v34, v12, v3, s50
	v_mul_f32_e32 v3, v41, v4
	v_cvt_pk_bf16_f32 v3, v3, s0
	v_alignbit_b32 v35, v3, v12, 16
	ds_write_b64 v1, v[34:35] offset:80
	v_mul_f32_e32 v3, v42, v4
	v_pk_mul_f32 v[34:35], v[84:85], v[4:5] op_sel_hi:[1,0]
	v_cvt_pk_bf16_f32 v3, v3, s0
	v_cvt_pk_bf16_f32 v12, v34, v35
	v_perm_b32 v34, v12, v3, s50
	v_mul_f32_e32 v3, v45, v4
	v_cvt_pk_bf16_f32 v3, v3, s0
	v_alignbit_b32 v35, v3, v12, 16
	v_mul_f32_e32 v3, v46, v4
	v_pk_mul_f32 v[38:39], v[82:83], v[4:5] op_sel_hi:[1,0]
	ds_write_b64 v1, v[34:35] offset:96
	v_cvt_pk_bf16_f32 v3, v3, s0
	v_or_b32_e32 v34, 16, v98
	v_mov_b32_e32 v35, s2
	v_cvt_pk_bf16_f32 v12, v38, v39
	v_lshlrev_b64 v[60:61], 11, v[34:35]
	v_perm_b32 v38, v12, v3, s50
	v_mul_f32_e32 v3, v49, v4
	v_or_b32_e32 v60, v60, v11
	v_cvt_pk_bf16_f32 v3, v3, s0
	v_lshl_add_u64 v[46:47], s[10:11], 0, v[60:61]
	v_alignbit_b32 v39, v3, v12, 16
	global_load_dwordx4 v[34:37], v[46:47], off nt
	ds_write_b64 v1, v[38:39] offset:112
	v_mad_u32_u24 v3, v7, s49, v8
	ds_read_b128 v[42:45], v3
	ds_read_b128 v[82:85], v3 offset:1152
	global_load_dwordx4 v[38:41], v[100:101], off offset:128 nt
	s_waitcnt vmcnt(3)
	v_and_b32_e32 v7, 0xffff0000, v53
	v_or_b32_e32 v98, 24, v98
	s_waitcnt lgkmcnt(1)
	v_and_b32_e32 v8, 0xffff0000, v45
	v_mul_f32_e32 v7, v8, v7
	v_lshlrev_b32_e32 v8, 16, v53
	v_lshlrev_b32_e32 v12, 16, v45
	v_mul_f32_e32 v8, v12, v8
	v_cvt_pk_bf16_f32 v45, v8, v7
	v_and_b32_e32 v7, 0xffff0000, v52
	v_and_b32_e32 v8, 0xffff0000, v44
	v_mul_f32_e32 v7, v8, v7
	v_lshlrev_b32_e32 v8, 16, v52
	v_lshlrev_b64 v[52:53], 11, v[98:99]
	v_or_b32_e32 v52, v52, v11
	v_lshl_add_u64 v[90:91], s[10:11], 0, v[52:53]
	global_load_dwordx4 v[86:89], v[90:91], off nt
	v_lshlrev_b32_e32 v12, 16, v44
	v_mul_f32_e32 v8, v12, v8
	v_cvt_pk_bf16_f32 v44, v8, v7
	v_and_b32_e32 v7, 0xffff0000, v51
	v_and_b32_e32 v8, 0xffff0000, v43
	v_mul_f32_e32 v7, v8, v7
	v_lshlrev_b32_e32 v8, 16, v51
	v_lshlrev_b32_e32 v11, 16, v43
	v_mul_f32_e32 v8, v11, v8
	v_cvt_pk_bf16_f32 v43, v8, v7
	v_and_b32_e32 v7, 0xffff0000, v50
	v_and_b32_e32 v8, 0xffff0000, v42
	v_mul_f32_e32 v7, v8, v7
	v_lshlrev_b32_e32 v8, 16, v50
	v_lshlrev_b32_e32 v11, 16, v42
	v_mul_f32_e32 v8, v11, v8
	v_cvt_pk_bf16_f32 v42, v8, v7
	s_waitcnt lgkmcnt(0)
	v_and_b32_e32 v8, 0xffff0000, v85
	v_lshlrev_b32_e32 v11, 16, v85
	v_lshl_add_u64 v[50:51], s[8:9], 0, v[96:97]
	global_store_dwordx4 v[50:51], v[42:45], off
	global_load_dwordx4 v[42:45], v[62:63], off offset:128 nt
	v_lshl_add_u64 v[60:61], s[8:9], 0, v[60:61]
	global_load_dwordx4 v[46:49], v[46:47], off offset:128 nt
	s_waitcnt vmcnt(6)
	v_and_b32_e32 v7, 0xffff0000, v57
	v_mul_f32_e32 v7, v8, v7
	v_lshlrev_b32_e32 v8, 16, v57
	v_mul_f32_e32 v8, v11, v8
	v_cvt_pk_bf16_f32 v65, v8, v7
	v_and_b32_e32 v7, 0xffff0000, v56
	v_and_b32_e32 v8, 0xffff0000, v84
	v_mul_f32_e32 v7, v8, v7
	v_lshlrev_b32_e32 v8, 16, v56
	v_lshlrev_b32_e32 v11, 16, v84
	v_mul_f32_e32 v8, v11, v8
	v_cvt_pk_bf16_f32 v64, v8, v7
	v_and_b32_e32 v7, 0xffff0000, v55
	v_and_b32_e32 v8, 0xffff0000, v83
	v_mul_f32_e32 v7, v8, v7
	v_lshlrev_b32_e32 v8, 16, v55
	v_lshlrev_b32_e32 v11, 16, v83
	v_mul_f32_e32 v8, v11, v8
	v_cvt_pk_bf16_f32 v63, v8, v7
	v_and_b32_e32 v7, 0xffff0000, v54
	v_and_b32_e32 v8, 0xffff0000, v82
	v_mul_f32_e32 v7, v8, v7
	v_lshlrev_b32_e32 v8, 16, v54
	v_lshl_add_u64 v[54:55], s[8:9], 0, v[58:59]
	ds_read_b128 v[56:59], v3 offset:2304
	v_lshlrev_b32_e32 v11, 16, v82
	v_mul_f32_e32 v8, v11, v8
	v_cvt_pk_bf16_f32 v62, v8, v7
	global_store_dwordx4 v[54:55], v[62:65], off
	ds_read_b128 v[62:65], v3 offset:3456
	s_waitcnt lgkmcnt(1)
	v_and_b32_e32 v8, 0xffff0000, v59
	v_lshlrev_b32_e32 v11, 16, v59
	v_mul_f32_e32 v2, v2, v4
	v_cvt_pk_bf16_f32 v2, v2, s0
	s_waitcnt vmcnt(6)
	v_and_b32_e32 v7, 0xffff0000, v37
	v_mul_f32_e32 v7, v8, v7
	v_lshlrev_b32_e32 v8, 16, v37
	v_mul_f32_e32 v8, v11, v8
	v_cvt_pk_bf16_f32 v37, v8, v7
	v_and_b32_e32 v7, 0xffff0000, v36
	v_and_b32_e32 v8, 0xffff0000, v58
	v_mul_f32_e32 v7, v8, v7
	v_lshlrev_b32_e32 v8, 16, v36
	v_lshlrev_b32_e32 v11, 16, v58
	v_mul_f32_e32 v8, v11, v8
	v_cvt_pk_bf16_f32 v36, v8, v7
	v_and_b32_e32 v7, 0xffff0000, v35
	v_and_b32_e32 v8, 0xffff0000, v57
	v_mul_f32_e32 v7, v8, v7
	v_lshlrev_b32_e32 v8, 16, v35
	v_lshlrev_b32_e32 v11, 16, v57
	v_mul_f32_e32 v8, v11, v8
	v_cvt_pk_bf16_f32 v35, v8, v7
	v_and_b32_e32 v7, 0xffff0000, v34
	v_and_b32_e32 v8, 0xffff0000, v56
	v_mul_f32_e32 v7, v8, v7
	v_lshlrev_b32_e32 v8, 16, v34
	v_lshlrev_b32_e32 v11, 16, v56
	v_mul_f32_e32 v8, v11, v8
	v_cvt_pk_bf16_f32 v34, v8, v7
	global_store_dwordx4 v[60:61], v[34:37], off
	global_load_dwordx4 v[34:37], v[90:91], off offset:128 nt
	s_waitcnt vmcnt(6)
	v_and_b32_e32 v7, 0xffff0000, v89
	s_waitcnt lgkmcnt(0)
	v_and_b32_e32 v8, 0xffff0000, v65
	v_mul_f32_e32 v7, v8, v7
	v_lshlrev_b32_e32 v8, 16, v89
	v_lshlrev_b32_e32 v11, 16, v65
	v_mul_f32_e32 v8, v11, v8
	v_cvt_pk_bf16_f32 v59, v8, v7
	v_and_b32_e32 v7, 0xffff0000, v88
	v_and_b32_e32 v8, 0xffff0000, v64
	v_mul_f32_e32 v7, v8, v7
	v_lshlrev_b32_e32 v8, 16, v88
	v_lshlrev_b32_e32 v11, 16, v64
	v_mul_f32_e32 v8, v11, v8
	v_cvt_pk_bf16_f32 v58, v8, v7
	v_and_b32_e32 v7, 0xffff0000, v87
	v_and_b32_e32 v8, 0xffff0000, v63
	v_mul_f32_e32 v7, v8, v7
	v_lshlrev_b32_e32 v8, 16, v87
	v_lshlrev_b32_e32 v11, 16, v63
	v_mul_f32_e32 v8, v11, v8
	v_cvt_pk_bf16_f32 v57, v8, v7
	v_and_b32_e32 v7, 0xffff0000, v86
	v_and_b32_e32 v8, 0xffff0000, v62
	v_mul_f32_e32 v7, v8, v7
	v_lshlrev_b32_e32 v8, 16, v86
	v_lshlrev_b32_e32 v11, 16, v62
	v_mul_f32_e32 v8, v11, v8
	v_cvt_pk_bf16_f32 v56, v8, v7
	v_mul_f32_e32 v7, v18, v4
	v_pk_mul_f32 v[18:19], v[80:81], v[4:5] op_sel_hi:[1,0]
	v_cvt_pk_bf16_f32 v7, v7, s0
	v_cvt_pk_bf16_f32 v8, v18, v19
	v_perm_b32 v18, v8, v7, s50
	v_mul_f32_e32 v7, v21, v4
	v_cvt_pk_bf16_f32 v7, v7, s0
	v_alignbit_b32 v19, v7, v8, 16
	ds_write_b64 v1, v[18:19]
	v_mul_f32_e32 v7, v22, v4
	v_pk_mul_f32 v[18:19], v[78:79], v[4:5] op_sel_hi:[1,0]
	v_cvt_pk_bf16_f32 v7, v7, s0
	v_cvt_pk_bf16_f32 v8, v18, v19
	v_perm_b32 v18, v8, v7, s50
	v_mul_f32_e32 v7, v25, v4
	v_cvt_pk_bf16_f32 v7, v7, s0
	v_alignbit_b32 v19, v7, v8, 16
	ds_write_b64 v1, v[18:19] offset:16
	v_mul_f32_e32 v7, v26, v4
	v_pk_mul_f32 v[18:19], v[76:77], v[4:5] op_sel_hi:[1,0]
	v_cvt_pk_bf16_f32 v7, v7, s0
	v_cvt_pk_bf16_f32 v8, v18, v19
	v_perm_b32 v18, v8, v7, s50
	v_mul_f32_e32 v7, v29, v4
	v_cvt_pk_bf16_f32 v7, v7, s0
	v_alignbit_b32 v19, v7, v8, 16
	ds_write_b64 v1, v[18:19] offset:32
	v_mul_f32_e32 v7, v30, v4
	v_pk_mul_f32 v[18:19], v[74:75], v[4:5] op_sel_hi:[1,0]
	v_cvt_pk_bf16_f32 v7, v7, s0
	v_cvt_pk_bf16_f32 v8, v18, v19
	v_perm_b32 v18, v8, v7, s50
	v_mul_f32_e32 v7, v33, v4
	v_cvt_pk_bf16_f32 v7, v7, s0
	v_alignbit_b32 v19, v7, v8, 16
	ds_write_b64 v1, v[18:19] offset:48
	v_pk_mul_f32 v[18:19], v[72:73], v[4:5] op_sel_hi:[1,0]
	s_add_i32 s51, s51, s42
	v_cvt_pk_bf16_f32 v7, v18, v19
	v_perm_b32 v18, v7, v2, s50
	v_mul_f32_e32 v2, v5, v4
	v_cvt_pk_bf16_f32 v2, v2, s0
	v_alignbit_b32 v19, v2, v7, 16
	v_mul_f32_e32 v2, v6, v4
	v_pk_mul_f32 v[6:7], v[70:71], v[4:5] op_sel_hi:[1,0]
	v_cvt_pk_bf16_f32 v2, v2, s0
	v_cvt_pk_bf16_f32 v5, v6, v7
	v_perm_b32 v6, v5, v2, s50
	v_mul_f32_e32 v2, v9, v4
	v_cvt_pk_bf16_f32 v2, v2, s0
	v_alignbit_b32 v7, v2, v5, 16
	ds_write_b64 v1, v[6:7] offset:80
	v_mul_f32_e32 v2, v10, v4
	v_pk_mul_f32 v[6:7], v[68:69], v[4:5] op_sel_hi:[1,0]
	v_cvt_pk_bf16_f32 v2, v2, s0
	v_cvt_pk_bf16_f32 v5, v6, v7
	v_perm_b32 v6, v5, v2, s50
	v_mul_f32_e32 v2, v13, v4
	v_cvt_pk_bf16_f32 v2, v2, s0
	v_alignbit_b32 v7, v2, v5, 16
	ds_write_b64 v1, v[6:7] offset:96
	v_mul_f32_e32 v2, v14, v4
	v_pk_mul_f32 v[6:7], v[66:67], v[4:5] op_sel_hi:[1,0]
	v_cvt_pk_bf16_f32 v2, v2, s0
	v_cvt_pk_bf16_f32 v5, v6, v7
	v_perm_b32 v6, v5, v2, s50
	v_mul_f32_e32 v2, v17, v4
	v_cvt_pk_bf16_f32 v2, v2, s0
	v_alignbit_b32 v7, v2, v5, 16
	ds_write_b64 v1, v[18:19] offset:64
	ds_write_b64 v1, v[6:7] offset:112
	ds_read_b128 v[4:7], v3
	ds_read_b128 v[8:11], v3 offset:1152
	v_and_b32_e32 v1, 0xffff0000, v41
	v_lshl_add_u64 v[12:13], s[8:9], 0, v[52:53]
	global_store_dwordx4 v[12:13], v[56:59], off
	s_waitcnt lgkmcnt(1)
	v_and_b32_e32 v2, 0xffff0000, v7
	v_mul_f32_e32 v1, v2, v1
	v_lshlrev_b32_e32 v2, 16, v41
	v_lshlrev_b32_e32 v7, 16, v7
	v_mul_f32_e32 v2, v7, v2
	v_cvt_pk_bf16_f32 v7, v2, v1
	v_and_b32_e32 v1, 0xffff0000, v40
	v_and_b32_e32 v2, 0xffff0000, v6
	v_mul_f32_e32 v1, v2, v1
	v_lshlrev_b32_e32 v2, 16, v40
	v_lshlrev_b32_e32 v6, 16, v6
	v_mul_f32_e32 v2, v6, v2
	v_cvt_pk_bf16_f32 v6, v2, v1
	v_and_b32_e32 v1, 0xffff0000, v39
	v_and_b32_e32 v2, 0xffff0000, v5
	v_mul_f32_e32 v1, v2, v1
	v_lshlrev_b32_e32 v2, 16, v39
	v_lshlrev_b32_e32 v5, 16, v5
	v_mul_f32_e32 v2, v5, v2
	v_cvt_pk_bf16_f32 v5, v2, v1
	v_and_b32_e32 v1, 0xffff0000, v38
	v_and_b32_e32 v2, 0xffff0000, v4
	v_mul_f32_e32 v1, v2, v1
	v_lshlrev_b32_e32 v2, 16, v38
	v_lshlrev_b32_e32 v4, 16, v4
	v_mul_f32_e32 v2, v4, v2
	v_cvt_pk_bf16_f32 v4, v2, v1
	s_waitcnt vmcnt(5)
	v_and_b32_e32 v1, 0xffff0000, v45
	s_waitcnt lgkmcnt(0)
	v_and_b32_e32 v2, 0xffff0000, v11
	global_store_dwordx4 v[50:51], v[4:7], off offset:128
	v_mul_f32_e32 v1, v2, v1
	v_lshlrev_b32_e32 v2, 16, v45
	v_lshlrev_b32_e32 v4, 16, v11
	v_mul_f32_e32 v2, v4, v2
	v_cvt_pk_bf16_f32 v7, v2, v1
	v_and_b32_e32 v1, 0xffff0000, v44
	v_and_b32_e32 v2, 0xffff0000, v10
	v_mul_f32_e32 v1, v2, v1
	v_lshlrev_b32_e32 v2, 16, v44
	v_lshlrev_b32_e32 v4, 16, v10
	v_mul_f32_e32 v2, v4, v2
	v_cvt_pk_bf16_f32 v6, v2, v1
	v_and_b32_e32 v1, 0xffff0000, v43
	v_and_b32_e32 v2, 0xffff0000, v9
	v_mul_f32_e32 v1, v2, v1
	v_lshlrev_b32_e32 v2, 16, v43
	v_lshlrev_b32_e32 v4, 16, v9
	v_mul_f32_e32 v2, v4, v2
	v_cvt_pk_bf16_f32 v5, v2, v1
	v_and_b32_e32 v2, 0xffff0000, v8
	v_lshlrev_b32_e32 v4, 16, v8
	ds_read_b128 v[8:11], v3 offset:2304
	v_and_b32_e32 v1, 0xffff0000, v42
	v_mul_f32_e32 v1, v2, v1
	v_lshlrev_b32_e32 v2, 16, v42
	v_mul_f32_e32 v2, v4, v2
	v_cvt_pk_bf16_f32 v4, v2, v1
	global_store_dwordx4 v[54:55], v[4:7], off offset:128
	s_waitcnt vmcnt(6)
	v_and_b32_e32 v1, 0xffff0000, v49
	ds_read_b128 v[2:5], v3 offset:3456
	s_waitcnt lgkmcnt(1)
	v_and_b32_e32 v6, 0xffff0000, v11
	v_mul_f32_e32 v1, v6, v1
	v_lshlrev_b32_e32 v6, 16, v49
	v_lshlrev_b32_e32 v7, 16, v11
	v_mul_f32_e32 v6, v7, v6
	v_cvt_pk_bf16_f32 v11, v6, v1
	v_and_b32_e32 v1, 0xffff0000, v48
	v_and_b32_e32 v6, 0xffff0000, v10
	v_mul_f32_e32 v1, v6, v1
	v_lshlrev_b32_e32 v6, 16, v48
	v_lshlrev_b32_e32 v7, 16, v10
	v_mul_f32_e32 v6, v7, v6
	v_cvt_pk_bf16_f32 v10, v6, v1
	v_and_b32_e32 v1, 0xffff0000, v47
	v_and_b32_e32 v6, 0xffff0000, v9
	v_mul_f32_e32 v1, v6, v1
	v_lshlrev_b32_e32 v6, 16, v47
	v_lshlrev_b32_e32 v7, 16, v9
	v_mul_f32_e32 v6, v7, v6
	v_cvt_pk_bf16_f32 v9, v6, v1
	v_and_b32_e32 v1, 0xffff0000, v46
	v_and_b32_e32 v6, 0xffff0000, v8
	v_mul_f32_e32 v1, v6, v1
	v_lshlrev_b32_e32 v6, 16, v46
	v_lshlrev_b32_e32 v7, 16, v8
	v_mul_f32_e32 v6, v7, v6
	v_cvt_pk_bf16_f32 v8, v6, v1
	s_waitcnt vmcnt(3)
	v_and_b32_e32 v1, 0xffff0000, v37
	s_waitcnt lgkmcnt(0)
	v_and_b32_e32 v6, 0xffff0000, v5
	v_mul_f32_e32 v1, v6, v1
	v_lshlrev_b32_e32 v6, 16, v37
	v_lshlrev_b32_e32 v5, 16, v5
	v_mul_f32_e32 v5, v5, v6
	v_cvt_pk_bf16_f32 v5, v5, v1
	v_and_b32_e32 v1, 0xffff0000, v36
	v_and_b32_e32 v6, 0xffff0000, v4
	v_mul_f32_e32 v1, v6, v1
	v_lshlrev_b32_e32 v6, 16, v36
	v_lshlrev_b32_e32 v4, 16, v4
	v_mul_f32_e32 v4, v4, v6
	v_cvt_pk_bf16_f32 v4, v4, v1
	v_and_b32_e32 v1, 0xffff0000, v35
	v_and_b32_e32 v6, 0xffff0000, v3
	v_mul_f32_e32 v1, v6, v1
	v_lshlrev_b32_e32 v6, 16, v35
	v_lshlrev_b32_e32 v3, 16, v3
	v_mul_f32_e32 v3, v3, v6
	v_cvt_pk_bf16_f32 v3, v3, v1
	v_and_b32_e32 v1, 0xffff0000, v34
	v_and_b32_e32 v6, 0xffff0000, v2
	v_mul_f32_e32 v1, v6, v1
	v_lshlrev_b32_e32 v6, 16, v34
	v_lshlrev_b32_e32 v2, 16, v2
	v_mul_f32_e32 v2, v2, v6
	v_cvt_pk_bf16_f32 v2, v2, v1
	s_cmpk_lt_i32 s51, 0x400
	global_store_dwordx4 v[60:61], v[8:11], off offset:128
	global_store_dwordx4 v[12:13], v[2:5], off offset:128
	s_cbranch_scc0 .LBB0_1213

.LBB0_2136:
	s_load_dwordx2 s[2:3], s[0:1], 0x68
	s_load_dwordx4 s[8:11], s[0:1], 0x158
	s_ashr_i32 s21, s20, 31
	s_lshl_b64 s[20:21], s[20:21], 2
	v_mov_b32_e32 v4, v91
	s_waitcnt lgkmcnt(0)
	s_add_u32 s2, s2, s20
	s_addc_u32 s3, s3, s21
	global_load_dword v0, v1, s[2:3]
	v_mov_b32_e32 v53, s17
	v_lshlrev_b32_e32 v12, 3, v4
	v_bfe_u32 v15, v4, 3, 3
	v_and_b32_e32 v16, 56, v12
	v_or_b32_e32 v52, s16, v15
	v_mov_b32_e32 v51, s19
	v_mov_b32_e32 v55, s17
	v_or_b32_e32 v50, s18, v16
	v_lshlrev_b64 v[56:57], 10, v[52:53]
	v_or_b32_e32 v54, 8, v52
	v_lshl_add_u64 v[56:57], v[56:57], 0, v[50:51]
	v_lshlrev_b64 v[54:55], 10, v[54:55]
	v_lshlrev_b64 v[62:63], 1, v[56:57]
	v_lshl_add_u64 v[54:55], v[54:55], 0, v[50:51]
	v_lshl_add_u64 v[64:65], s[10:11], 0, v[62:63]
	s_waitcnt vmcnt(2)
	v_lshlrev_b64 v[66:67], 1, v[54:55]
	v_lshl_add_u64 v[68:69], s[10:11], 0, v[66:67]
	global_load_dwordx4 v[54:57], v[64:65], off nt
	global_load_dwordx4 v[58:61], v[68:69], off nt
	ds_bpermute_b32 v3, v98, v101
	v_add_u32_e32 v7, s70, v4
	v_and_b32_e32 v8, 31, v4
	v_readfirstlane_b32 s2, v7
	s_lshr_b32 s2, s2, 6
	s_mulk_i32 s2, 0x1200
	s_waitcnt lgkmcnt(0)
	v_add_f32_e32 v3, v101, v3
	s_add_i32 s14, s2, 0x18000
	v_lshrrev_b32_e32 v11, 2, v4
	v_mov_b32_e32 v4, s14
	v_mad_u32_u24 v4, v8, s28, v4
	v_and_or_b32 v20, v11, 8, v4
	s_add_i32 s24, s24, s42
	s_add_i32 s26, s26, s27
	s_cmpk_lt_i32 s24, 0x800
	s_waitcnt vmcnt(2)
	v_fma_f32 v0, v0, s31, -v105
	v_exp_f32_e32 v0, v0
	s_nop 0
	v_add_f32_e32 v0, v3, v0
	v_div_scale_f32 v3, s[2:3], v0, v0, 1.0
	v_rcp_f32_e32 v4, v3
	v_div_scale_f32 v7, vcc, 1.0, v0, 1.0
	v_fma_f32 v8, -v3, v4, 1.0
	v_fmac_f32_e32 v4, v8, v4
	v_mul_f32_e32 v8, v7, v4
	v_fma_f32 v11, -v3, v8, v7
	v_fmac_f32_e32 v8, v11, v4
	v_fma_f32 v3, -v3, v8, v7
	v_div_fmas_f32 v3, v3, v4, v8
	v_div_fixup_f32 v0, v3, v0, 1.0
	v_mul_f32_e32 v19, v2, v0
	v_pk_mul_f32 v[2:3], v[48:49], v[0:1] op_sel_hi:[1,0]
	v_mul_f32_e32 v23, v5, v0
	v_mul_f32_e32 v24, v6, v0
	v_pk_mul_f32 v[4:5], v[46:47], v[0:1] op_sel_hi:[1,0]
	v_mul_f32_e32 v27, v9, v0
	v_mul_f32_e32 v28, v10, v0
	v_pk_mul_f32 v[6:7], v[44:45], v[0:1] op_sel_hi:[1,0]
	v_mul_f32_e32 v31, v13, v0
	v_mul_f32_e32 v14, v14, v0
	v_pk_mul_f32 v[8:9], v[42:43], v[0:1] op_sel_hi:[1,0]
	v_mul_f32_e32 v17, v17, v0
	v_mul_f32_e32 v18, v18, v0
	v_pk_mul_f32 v[10:11], v[40:41], v[0:1] op_sel_hi:[1,0]
	v_mul_f32_e32 v21, v21, v0
	v_mul_f32_e32 v22, v22, v0
	v_pk_mul_f32 v[12:13], v[38:39], v[0:1] op_sel_hi:[1,0]
	v_mul_f32_e32 v25, v25, v0
	v_cvt_pk_bf16_f32 v19, v19, s0
	v_cvt_pk_bf16_f32 v3, v2, v3
	v_cvt_pk_bf16_f32 v23, v23, s0
	v_cvt_pk_bf16_f32 v24, v24, s0
	v_cvt_pk_bf16_f32 v5, v4, v5
	v_cvt_pk_bf16_f32 v27, v27, s0
	v_cvt_pk_bf16_f32 v28, v28, s0
	v_cvt_pk_bf16_f32 v7, v6, v7
	v_cvt_pk_bf16_f32 v31, v31, s0
	v_cvt_pk_bf16_f32 v14, v14, s0
	v_cvt_pk_bf16_f32 v9, v8, v9
	v_cvt_pk_bf16_f32 v17, v17, s0
	v_cvt_pk_bf16_f32 v18, v18, s0
	v_cvt_pk_bf16_f32 v11, v10, v11
	v_cvt_pk_bf16_f32 v21, v21, s0
	v_cvt_pk_bf16_f32 v22, v22, s0
	v_cvt_pk_bf16_f32 v13, v12, v13
	v_cvt_pk_bf16_f32 v25, v25, s0
	v_perm_b32 v2, v3, v19, s34
	v_alignbit_b32 v3, v23, v3, 16
	v_perm_b32 v4, v5, v24, s34
	v_alignbit_b32 v5, v27, v5, 16
	v_perm_b32 v6, v7, v28, s34
	v_alignbit_b32 v7, v31, v7, 16
	v_perm_b32 v8, v9, v14, s34
	v_alignbit_b32 v9, v17, v9, 16
	v_perm_b32 v10, v11, v18, s34
	v_alignbit_b32 v11, v21, v11, 16
	v_perm_b32 v12, v13, v22, s34
	v_alignbit_b32 v13, v25, v13, 16
	ds_write2_b64 v20, v[2:3], v[4:5] offset1:2
	ds_write2_b64 v20, v[6:7], v[8:9] offset0:4 offset1:6
	ds_write2_b64 v20, v[10:11], v[12:13] offset0:8 offset1:10
	v_pk_mul_f32 v[2:3], v[36:37], v[0:1] op_sel_hi:[1,0]
	v_mul_f32_e32 v26, v26, v0
	v_cvt_pk_bf16_f32 v2, v2, v3
	v_mul_f32_e32 v3, v29, v0
	v_cvt_pk_bf16_f32 v26, v26, s0
	v_cvt_pk_bf16_f32 v3, v3, s0
	v_perm_b32 v6, v2, v26, s34
	v_alignbit_b32 v7, v3, v2, 16
	v_mul_f32_e32 v2, v30, v0
	v_pk_mul_f32 v[8:9], v[34:35], v[0:1] op_sel_hi:[1,0]
	v_mul_f32_e32 v0, v33, v0
	v_cvt_pk_bf16_f32 v10, v2, s0
	v_cvt_pk_bf16_f32 v9, v8, v9
	v_cvt_pk_bf16_f32 v0, v0, s0
	v_perm_b32 v8, v9, v10, s34
	v_alignbit_b32 v9, v0, v9, 16
	v_lshl_or_b32 v0, v16, 1, s14
	ds_write2_b64 v20, v[6:7], v[8:9] offset0:12 offset1:14
	v_mad_u32_u24 v0, v15, s28, v0
	ds_read_b128 v[6:9], v0
	ds_read_b128 v[10:13], v0 offset:1152
	v_or_b32_e32 v2, 16, v52
	v_mov_b32_e32 v3, s17
	v_lshlrev_b64 v[2:3], 10, v[2:3]
	v_lshl_add_u64 v[2:3], v[2:3], 0, v[50:51]
	v_lshlrev_b64 v[18:19], 1, v[2:3]
	v_lshl_add_u64 v[2:3], s[10:11], 0, v[18:19]
	s_waitcnt vmcnt(1)
	v_and_b32_e32 v14, 0xffff0000, v57
	s_waitcnt lgkmcnt(1)
	v_and_b32_e32 v15, 0xffff0000, v9
	global_load_dwordx4 v[2:5], v[2:3], off nt
	v_mul_f32_e32 v14, v15, v14
	v_lshlrev_b32_e32 v15, 16, v57
	v_lshlrev_b32_e32 v9, 16, v9
	v_mul_f32_e32 v9, v9, v15
	v_cvt_pk_bf16_f32 v9, v9, v14
	v_and_b32_e32 v14, 0xffff0000, v56
	v_and_b32_e32 v15, 0xffff0000, v8
	v_mul_f32_e32 v14, v15, v14
	v_lshlrev_b32_e32 v15, 16, v56
	v_lshlrev_b32_e32 v8, 16, v8
	v_mul_f32_e32 v8, v8, v15
	v_or_b32_e32 v52, 24, v52
	v_cvt_pk_bf16_f32 v8, v8, v14
	v_lshlrev_b64 v[14:15], 10, v[52:53]
	v_lshl_add_u64 v[14:15], v[14:15], 0, v[50:51]
	v_lshlrev_b64 v[20:21], 1, v[14:15]
	v_lshl_add_u64 v[14:15], s[10:11], 0, v[20:21]
	global_load_dwordx4 v[14:17], v[14:15], off nt
	v_and_b32_e32 v22, 0xffff0000, v55
	v_and_b32_e32 v23, 0xffff0000, v7
	v_mul_f32_e32 v22, v23, v22
	v_lshlrev_b32_e32 v23, 16, v55
	v_lshlrev_b32_e32 v7, 16, v7
	v_mul_f32_e32 v7, v7, v23
	v_cvt_pk_bf16_f32 v7, v7, v22
	v_and_b32_e32 v22, 0xffff0000, v54
	v_and_b32_e32 v23, 0xffff0000, v6
	v_mul_f32_e32 v22, v23, v22
	v_lshlrev_b32_e32 v23, 16, v54
	v_lshlrev_b32_e32 v6, 16, v6
	v_mul_f32_e32 v6, v6, v23
	v_cvt_pk_bf16_f32 v6, v6, v22
	v_lshl_add_u64 v[22:23], s[8:9], 0, v[62:63]
	global_store_dwordx4 v[22:23], v[6:9], off
	v_lshl_add_u64 v[22:23], s[8:9], 0, v[66:67]
	s_waitcnt vmcnt(3)
	v_and_b32_e32 v6, 0xffff0000, v61
	s_waitcnt lgkmcnt(0)
	v_and_b32_e32 v7, 0xffff0000, v13
	v_mul_f32_e32 v6, v7, v6
	v_lshlrev_b32_e32 v7, 16, v61
	v_lshlrev_b32_e32 v8, 16, v13
	v_mul_f32_e32 v7, v8, v7
	v_cvt_pk_bf16_f32 v9, v7, v6
	v_and_b32_e32 v6, 0xffff0000, v60
	v_and_b32_e32 v7, 0xffff0000, v12
	v_mul_f32_e32 v6, v7, v6
	v_lshlrev_b32_e32 v7, 16, v60
	v_lshlrev_b32_e32 v8, 16, v12
	v_mul_f32_e32 v7, v8, v7
	v_cvt_pk_bf16_f32 v8, v7, v6
	v_and_b32_e32 v6, 0xffff0000, v59
	v_and_b32_e32 v7, 0xffff0000, v11
	v_mul_f32_e32 v6, v7, v6
	v_lshlrev_b32_e32 v7, 16, v59
	v_lshlrev_b32_e32 v11, 16, v11
	v_mul_f32_e32 v7, v11, v7
	v_cvt_pk_bf16_f32 v7, v7, v6
	v_and_b32_e32 v6, 0xffff0000, v58
	v_and_b32_e32 v11, 0xffff0000, v10
	v_mul_f32_e32 v6, v11, v6
	v_lshlrev_b32_e32 v11, 16, v58
	v_lshlrev_b32_e32 v10, 16, v10
	v_mul_f32_e32 v10, v10, v11
	v_cvt_pk_bf16_f32 v6, v10, v6
	ds_read_b128 v[10:13], v0 offset:2304
	global_store_dwordx4 v[22:23], v[6:9], off
	ds_read_b128 v[6:9], v0 offset:3456
	s_waitcnt lgkmcnt(1)
	v_and_b32_e32 v0, 0xffff0000, v13
	v_lshlrev_b32_e32 v13, 16, v13
	s_waitcnt vmcnt(3)
	v_and_b32_e32 v22, 0xffff0000, v5
	v_lshlrev_b32_e32 v5, 16, v5
	v_mul_f32_e32 v0, v0, v22
	v_mul_f32_e32 v5, v13, v5
	v_cvt_pk_bf16_f32 v5, v5, v0
	v_and_b32_e32 v0, 0xffff0000, v4
	v_and_b32_e32 v13, 0xffff0000, v12
	v_lshlrev_b32_e32 v4, 16, v4
	v_lshlrev_b32_e32 v12, 16, v12
	v_mul_f32_e32 v0, v13, v0
	v_mul_f32_e32 v4, v12, v4
	v_cvt_pk_bf16_f32 v4, v4, v0
	v_and_b32_e32 v0, 0xffff0000, v3
	v_and_b32_e32 v12, 0xffff0000, v11
	v_lshlrev_b32_e32 v3, 16, v3
	v_lshlrev_b32_e32 v11, 16, v11
	v_mul_f32_e32 v0, v12, v0
	v_mul_f32_e32 v3, v11, v3
	v_cvt_pk_bf16_f32 v3, v3, v0
	v_and_b32_e32 v0, 0xffff0000, v2
	v_and_b32_e32 v11, 0xffff0000, v10
	v_lshlrev_b32_e32 v2, 16, v2
	v_lshlrev_b32_e32 v10, 16, v10
	v_mul_f32_e32 v0, v11, v0
	v_mul_f32_e32 v2, v10, v2
	v_cvt_pk_bf16_f32 v2, v2, v0
	v_lshl_add_u64 v[10:11], s[8:9], 0, v[18:19]
	global_store_dwordx4 v[10:11], v[2:5], off
	s_waitcnt lgkmcnt(0)
	v_and_b32_e32 v0, 0xffff0000, v9
	s_waitcnt vmcnt(3)
	v_and_b32_e32 v2, 0xffff0000, v17
	v_mul_f32_e32 v0, v0, v2
	v_lshlrev_b32_e32 v2, 16, v9
	v_lshlrev_b32_e32 v3, 16, v17
	v_mul_f32_e32 v2, v2, v3
	v_cvt_pk_bf16_f32 v5, v2, v0
	v_and_b32_e32 v0, 0xffff0000, v8
	v_and_b32_e32 v2, 0xffff0000, v16
	v_mul_f32_e32 v0, v0, v2
	v_lshlrev_b32_e32 v2, 16, v8
	v_lshlrev_b32_e32 v3, 16, v16
	v_mul_f32_e32 v2, v2, v3
	v_cvt_pk_bf16_f32 v4, v2, v0
	v_and_b32_e32 v0, 0xffff0000, v7
	v_and_b32_e32 v2, 0xffff0000, v15
	v_mul_f32_e32 v0, v0, v2
	v_lshlrev_b32_e32 v2, 16, v7
	v_lshlrev_b32_e32 v3, 16, v15
	v_mul_f32_e32 v2, v2, v3
	v_cvt_pk_bf16_f32 v3, v2, v0
	v_and_b32_e32 v0, 0xffff0000, v6
	v_and_b32_e32 v2, 0xffff0000, v14
	v_mul_f32_e32 v0, v0, v2
	v_lshlrev_b32_e32 v2, 16, v6
	v_lshlrev_b32_e32 v6, 16, v14
	v_mul_f32_e32 v2, v2, v6
	v_cvt_pk_bf16_f32 v2, v2, v0
	v_lshl_add_u64 v[6:7], s[8:9], 0, v[20:21]
	global_store_dwordx4 v[6:7], v[2:5], off
	s_cbranch_scc0 .LBB0_2157
